# proj phase: one continuous 16-K-tile staging loop per tile (was three segment pipelines with a drain each); segment gating + next gate loads in the loop latch, counted waits keep the gate loads in fli
# speedup vs baseline: 1.0898x; 1.0087x over previous
.LBB0_379:
	s_waitcnt vmcnt(0)
	s_cmp_eq_u32 s34, 2
	v_mov_b32_e32 v30, v135
	s_movk_i32 s35, 16
	s_lshl_b32 s44, s34, 9
	s_add_u32 s42, s26, s44
	v_ashrrev_i32_e32 v18, 3, v30
	v_ashrrev_i32_e32 v19, 31, v18
	s_addc_u32 s43, s29, 0
	v_lshlrev_b64 v[20:21], 11, v[18:19]
	v_lshlrev_b32_e32 v0, 4, v30
	s_add_u32 s44, s30, s44
	v_lshl_add_u64 v[2:3], s[42:43], 0, v[20:21]
	v_and_b32_e32 v0, 0x70, v0
	s_addc_u32 s45, s31, 0
	v_lshl_add_u64 v[22:23], v[2:3], 0, v[0:1]
	s_mov_b32 s4, 0x20000
	v_lshl_add_u64 v[2:3], s[44:45], 0, v[20:21]
	v_add_co_u32_e32 v26, vcc, s4, v22
	v_lshl_add_u64 v[24:25], v[2:3], 0, v[0:1]
	s_nop 0
	v_addc_co_u32_e32 v27, vcc, 0, v23, vcc
	global_load_dwordx4 v[2:5], v[22:23], off
	global_load_dwordx4 v[6:9], v[26:27], off
	global_load_dwordx4 v[10:13], v[24:25], off
	v_add_co_u32_e32 v28, vcc, s4, v24
	v_lshlrev_b32_e32 v0, 7, v18
	s_nop 0
	v_addc_co_u32_e32 v29, vcc, 0, v25, vcc
	global_load_dwordx4 v[14:17], v[28:29], off
	global_load_dwordx4 v[34:37], v[22:23], off offset:128
	global_load_dwordx4 v[38:41], v[26:27], off offset:128
	global_load_dwordx4 v[42:45], v[22:23], off offset:256
	global_load_dwordx4 v[46:49], v[26:27], off offset:256
	global_load_dwordx4 v[50:53], v[24:25], off offset:128
	global_load_dwordx4 v[54:57], v[24:25], off offset:256
	global_load_dwordx4 v[58:61], v[28:29], off offset:128
	global_load_dwordx4 v[62:65], v[28:29], off offset:256
	v_lshrrev_b32_e32 v18, 1, v18
	v_xor_b32_e32 v18, v18, v30
	v_lshlrev_b32_e32 v18, 4, v18
	v_and_b32_e32 v18, 0x70, v18
	v_add_u32_e32 v18, 0x50, v18
	v_add_u32_e32 v188, v18, v0
	s_movk_i32 s4, 0x3000
	v_lshrrev_b32_e32 v0, 5, v30
	v_lshl_add_u64 v[138:139], s[20:21], 0, v[20:21]
	v_lshl_add_u64 v[140:141], s[24:25], 0, v[20:21]
	v_lshl_add_u64 v[142:143], s[36:37], 0, v[20:21]
	v_lshl_add_u64 v[144:145], s[38:39], 0, v[20:21]
	v_lshl_add_u64 v[146:147], s[40:41], 0, v[20:21]
	s_mov_b32 s44, 0
	v_mov_b32_e32 v18, 0
	v_mov_b32_e32 v19, v77
	v_mov_b32_e32 v20, v77
	v_mov_b32_e32 v21, v77
	v_mov_b32_e32 v22, v77
	v_mov_b32_e32 v23, v77
	v_mov_b32_e32 v24, v77
	v_mov_b32_e32 v25, v77
	v_mov_b32_e32 v26, v77
	v_mov_b32_e32 v27, v77
	v_mov_b32_e32 v28, v77
	v_mov_b32_e32 v29, v77
	v_mov_b32_e32 v31, v77
	v_mov_b32_e32 v32, v77
	v_mov_b32_e32 v33, v77
	s_lshl_b32 s74, s34, 11
	v_lshl_add_u64 v[224:225], v[128:129], 0, s[74:75]
	v_lshl_add_u64 v[226:227], v[224:225], 0, v[88:89]
	s_mov_b64 s[8:9], 0x1800
	v_lshl_add_u64 v[228:229], v[226:227], 0, s[8:9]
	s_mov_b64 s[10:11], 0x1000
	v_lshl_add_u64 v[230:231], v[226:227], 0, s[10:11]
	v_lshl_add_u64 v[232:233], v[224:225], 0, v[90:91]
	v_lshl_add_u64 v[234:235], v[224:225], 0, v[92:93]
	v_lshl_add_u64 v[236:237], v[224:225], 0, v[96:97]
	v_lshl_add_u64 v[238:239], v[224:225], 0, v[98:99]
	v_lshl_add_u64 v[240:241], v[224:225], 0, v[100:101]
	v_lshl_add_u64 v[242:243], v[224:225], 0, v[104:105]
	v_lshl_add_u64 v[244:245], v[224:225], 0, v[106:107]
	v_lshl_add_u64 v[246:247], v[224:225], 0, v[108:109]
	v_lshl_add_u64 v[148:149], v[224:225], 0, v[112:113]
	v_lshl_add_u64 v[150:151], v[224:225], 0, v[114:115]
	v_lshl_add_u64 v[152:153], v[224:225], 0, v[116:117]
	v_lshl_add_u64 v[218:219], v[224:225], 0, v[120:121]
	v_lshl_add_u64 v[220:221], v[224:225], 0, v[122:123]
	v_lshl_add_u64 v[224:225], v[224:225], 0, v[124:125]
	global_load_ushort v162, v[226:227], off
	global_load_ushort v166, v[230:231], off offset:2048
	global_load_ushort v163, v[232:233], off
	global_load_ushort v167, v[234:235], off
	global_load_ushort v156, v[226:227], off offset:64
	global_load_ushort v158, v[234:235], off offset:64
	global_load_ushort v157, v[232:233], off offset:64
	global_load_ushort v159, v[228:229], off offset:64
	global_load_ushort v170, v[236:237], off
	global_load_ushort v174, v[238:239], off
	global_load_ushort v171, v[240:241], off
	global_load_ushort v175, v[242:243], off
	global_load_ushort v161, v[242:243], off offset:64
	global_load_ushort v160, v[240:241], off offset:64
	global_load_ushort v165, v[238:239], off offset:64
	global_load_ushort v164, v[236:237], off offset:64
	global_load_ushort v178, v[244:245], off
	global_load_ushort v182, v[246:247], off
	global_load_ushort v179, v[148:149], off
	global_load_ushort v183, v[150:151], off
	global_load_ushort v169, v[150:151], off offset:64
	global_load_ushort v168, v[148:149], off offset:64
	global_load_ushort v173, v[246:247], off offset:64
	global_load_ushort v172, v[244:245], off offset:64
	global_load_ushort v184, v[152:153], off
	global_load_ushort v186, v[218:219], off
	global_load_ushort v185, v[220:221], off
	global_load_ushort v187, v[224:225], off
	global_load_ushort v177, v[224:225], off offset:64
	global_load_ushort v176, v[220:221], off offset:64
	global_load_ushort v181, v[218:219], off offset:64
	global_load_ushort v180, v[152:153], off offset:64
	s_waitcnt vmcnt(43)
	ds_write_b128 v188, v[2:5]
	s_waitcnt vmcnt(42)
	ds_write_b128 v188, v[6:9] offset:8192
	s_waitcnt vmcnt(41)
	ds_write_b128 v188, v[10:13] offset:16384
	s_waitcnt vmcnt(40)
	ds_write_b128 v188, v[14:17] offset:24576
	v_lshlrev_b32_e32 v4, 7, v30
	v_lshlrev_b32_e32 v3, 6, v30
	v_and_b32_e32 v4, 0xf80, v4
	v_and_or_b32 v3, v3, s4, v4
	v_add_u32_e32 v189, 0x50, v3
	v_bfe_u32 v3, v30, 1, 3
	v_bitop3_b32 v0, v0, v3, 1 bitop3:0x6c
	v_bfe_u32 v2, v30, 5, 1
	v_lshlrev_b32_e32 v190, 4, v0
	v_lshlrev_b32_e32 v0, 5, v30
	s_movk_i32 s4, 0xe000
	v_and_or_b32 v4, v0, s4, v4
	v_bitop3_b32 v0, v2, v3, 2 bitop3:0x36
	v_lshlrev_b32_e32 v191, 4, v0
	v_bitop3_b32 v0, v2, v3, 4 bitop3:0x36
	v_lshlrev_b32_e32 v192, 4, v0
	v_bitop3_b32 v0, v2, v3, 6 bitop3:0x36
	v_lshlrev_b32_e32 v193, 4, v0
	v_add_u32_e32 v5, 0x50, v190
	v_add_u32_e32 v6, 0x50, v191
	v_add_u32_e32 v7, 0x50, v192
	v_add_u32_e32 v2, 0x50, v193
	v_and_b32_e32 v0, 7, v30
	v_lshlrev_b32_e32 v0, 4, v0
	v_add_u32_e32 v194, v5, v4
	v_add_u32_e32 v195, v6, v4
	v_add_u32_e32 v196, v7, v4
	v_add_u32_e32 v197, v2, v4
	v_mov_b32_e32 v30, v77
	v_mov_b32_e32 v2, 0
	v_mov_b32_e32 v3, v77
	v_mov_b32_e32 v4, v77
	v_mov_b32_e32 v5, v77
	v_mov_b32_e32 v6, v77
	v_mov_b32_e32 v7, v77
	v_mov_b32_e32 v8, v77
	v_mov_b32_e32 v9, v77
	v_mov_b32_e32 v10, v77
	v_mov_b32_e32 v11, v77
	v_mov_b32_e32 v12, v77
	v_mov_b32_e32 v13, v77
	v_mov_b32_e32 v14, v77
	v_mov_b32_e32 v15, v77
	v_mov_b32_e32 v16, v77
	v_mov_b32_e32 v17, v77
	s_waitcnt lgkmcnt(0)
	s_barrier
	s_branch .LBB0_381
.LBB0_380:
	v_lshl_add_u64 v[138:139], v[138:139], 0, s[80:81]
	v_lshl_add_u64 v[140:141], v[140:141], 0, s[80:81]
	v_lshl_add_u64 v[142:143], v[142:143], 0, s[80:81]
	v_lshl_add_u64 v[144:145], v[144:145], 0, s[80:81]
	v_lshl_add_u64 v[146:147], v[146:147], 0, s[80:81]
	s_cmp_eq_u32 s45, 4
	s_cbranch_scc1 .Lpc_mid
	s_cmp_eq_u32 s45, 8
	s_cbranch_scc0 .Lpc_nomid
.Lpc_mid:
	s_nop 7
	s_waitcnt vmcnt(8)
	v_lshlrev_b32_e32 v225, 16, v166
	v_lshlrev_b32_e32 v224, 16, v162
	v_lshlrev_b32_e32 v227, 16, v167
	v_lshlrev_b32_e32 v226, 16, v163
	v_lshlrev_b32_e32 v229, 16, v174
	v_lshlrev_b32_e32 v228, 16, v170
	v_lshlrev_b32_e32 v231, 16, v175
	v_lshlrev_b32_e32 v230, 16, v171
	v_lshlrev_b32_e32 v233, 16, v182
	v_lshlrev_b32_e32 v232, 16, v178
	v_lshlrev_b32_e32 v235, 16, v183
	v_lshlrev_b32_e32 v234, 16, v179
	v_lshlrev_b32_e32 v237, 16, v186
	v_lshlrev_b32_e32 v236, 16, v184
	v_lshlrev_b32_e32 v239, 16, v187
	v_lshlrev_b32_e32 v238, 16, v185
	v_lshlrev_b32_e32 v241, 16, v159
	v_lshlrev_b32_e32 v240, 16, v156
	v_lshlrev_b32_e32 v243, 16, v158
	v_lshlrev_b32_e32 v242, 16, v157
	v_lshlrev_b32_e32 v245, 16, v165
	v_lshlrev_b32_e32 v244, 16, v164
	v_lshlrev_b32_e32 v247, 16, v161
	v_lshlrev_b32_e32 v246, 16, v160
	v_lshlrev_b32_e32 v149, 16, v173
	v_lshlrev_b32_e32 v148, 16, v172
	v_lshlrev_b32_e32 v151, 16, v169
	v_lshlrev_b32_e32 v150, 16, v168
	v_lshlrev_b32_e32 v153, 16, v181
	v_lshlrev_b32_e32 v152, 16, v180
	v_lshlrev_b32_e32 v219, 16, v177
	v_lshlrev_b32_e32 v218, 16, v176
	v_pk_fma_f32 v[132:133], v[18:19], v[224:225], v[132:133]
	v_pk_fma_f32 v[130:131], v[20:21], v[226:227], v[130:131]
	v_pk_fma_f32 v[126:127], v[22:23], v[228:229], v[126:127]
	v_pk_fma_f32 v[118:119], v[24:25], v[230:231], v[118:119]
	v_pk_fma_f32 v[110:111], v[26:27], v[232:233], v[110:111]
	v_pk_fma_f32 v[102:103], v[28:29], v[234:235], v[102:103]
	v_pk_fma_f32 v[94:95], v[30:31], v[236:237], v[94:95]
	v_pk_fma_f32 v[84:85], v[32:33], v[238:239], v[84:85]
	v_pk_fma_f32 v[86:87], v[2:3], v[240:241], v[86:87]
	v_pk_fma_f32 v[82:83], v[4:5], v[242:243], v[82:83]
	v_pk_fma_f32 v[80:81], v[6:7], v[244:245], v[80:81]
	v_pk_fma_f32 v[78:79], v[8:9], v[246:247], v[78:79]
	v_pk_fma_f32 v[74:75], v[10:11], v[148:149], v[74:75]
	v_pk_fma_f32 v[72:73], v[12:13], v[150:151], v[72:73]
	v_pk_fma_f32 v[70:71], v[14:15], v[152:153], v[70:71]
	v_pk_fma_f32 v[66:67], v[16:17], v[218:219], v[66:67]
	v_mov_b32_e32 v2, 0
	v_mov_b32_e32 v3, 0
	v_mov_b32_e32 v4, 0
	v_mov_b32_e32 v5, 0
	v_mov_b32_e32 v6, 0
	v_mov_b32_e32 v7, 0
	v_mov_b32_e32 v8, 0
	v_mov_b32_e32 v9, 0
	v_mov_b32_e32 v10, 0
	v_mov_b32_e32 v11, 0
	v_mov_b32_e32 v12, 0
	v_mov_b32_e32 v13, 0
	v_mov_b32_e32 v14, 0
	v_mov_b32_e32 v15, 0
	v_mov_b32_e32 v16, 0
	v_mov_b32_e32 v17, 0
	v_mov_b32_e32 v18, 0
	v_mov_b32_e32 v19, 0
	v_mov_b32_e32 v20, 0
	v_mov_b32_e32 v21, 0
	v_mov_b32_e32 v22, 0
	v_mov_b32_e32 v23, 0
	v_mov_b32_e32 v24, 0
	v_mov_b32_e32 v25, 0
	v_mov_b32_e32 v26, 0
	v_mov_b32_e32 v27, 0
	v_mov_b32_e32 v28, 0
	v_mov_b32_e32 v29, 0
	v_mov_b32_e32 v30, 0
	v_mov_b32_e32 v31, 0
	v_mov_b32_e32 v32, 0
	v_mov_b32_e32 v33, 0
	s_add_i32 s34, s34, 1
	s_lshl_b32 s74, s34, 11
	v_lshl_add_u64 v[224:225], v[128:129], 0, s[74:75]
	v_lshl_add_u64 v[226:227], v[224:225], 0, v[88:89]
	s_mov_b64 s[8:9], 0x1800
	v_lshl_add_u64 v[228:229], v[226:227], 0, s[8:9]
	s_mov_b64 s[10:11], 0x1000
	v_lshl_add_u64 v[230:231], v[226:227], 0, s[10:11]
	v_lshl_add_u64 v[232:233], v[224:225], 0, v[90:91]
	v_lshl_add_u64 v[234:235], v[224:225], 0, v[92:93]
	v_lshl_add_u64 v[236:237], v[224:225], 0, v[96:97]
	v_lshl_add_u64 v[238:239], v[224:225], 0, v[98:99]
	v_lshl_add_u64 v[240:241], v[224:225], 0, v[100:101]
	v_lshl_add_u64 v[242:243], v[224:225], 0, v[104:105]
	v_lshl_add_u64 v[244:245], v[224:225], 0, v[106:107]
	v_lshl_add_u64 v[246:247], v[224:225], 0, v[108:109]
	v_lshl_add_u64 v[148:149], v[224:225], 0, v[112:113]
	v_lshl_add_u64 v[150:151], v[224:225], 0, v[114:115]
	v_lshl_add_u64 v[152:153], v[224:225], 0, v[116:117]
	v_lshl_add_u64 v[218:219], v[224:225], 0, v[120:121]
	v_lshl_add_u64 v[220:221], v[224:225], 0, v[122:123]
	v_lshl_add_u64 v[224:225], v[224:225], 0, v[124:125]
	global_load_ushort v162, v[226:227], off
	global_load_ushort v166, v[230:231], off offset:2048
	global_load_ushort v163, v[232:233], off
	global_load_ushort v167, v[234:235], off
	global_load_ushort v156, v[226:227], off offset:64
	global_load_ushort v158, v[234:235], off offset:64
	global_load_ushort v157, v[232:233], off offset:64
	global_load_ushort v159, v[228:229], off offset:64
	global_load_ushort v170, v[236:237], off
	global_load_ushort v174, v[238:239], off
	global_load_ushort v171, v[240:241], off
	global_load_ushort v175, v[242:243], off
	global_load_ushort v161, v[242:243], off offset:64
	global_load_ushort v160, v[240:241], off offset:64
	global_load_ushort v165, v[238:239], off offset:64
	global_load_ushort v164, v[236:237], off offset:64
	global_load_ushort v178, v[244:245], off
	global_load_ushort v182, v[246:247], off
	global_load_ushort v179, v[148:149], off
	global_load_ushort v183, v[150:151], off
	global_load_ushort v169, v[150:151], off offset:64
	global_load_ushort v168, v[148:149], off offset:64
	global_load_ushort v173, v[246:247], off offset:64
	global_load_ushort v172, v[244:245], off offset:64
	global_load_ushort v184, v[152:153], off
	global_load_ushort v186, v[218:219], off
	global_load_ushort v185, v[220:221], off
	global_load_ushort v187, v[224:225], off
	global_load_ushort v177, v[224:225], off offset:64
	global_load_ushort v176, v[220:221], off offset:64
	global_load_ushort v181, v[218:219], off offset:64
	global_load_ushort v180, v[152:153], off offset:64
.Lpc_nomid:
	s_andn2_b64 vcc, exec, s[42:43]
	s_mov_b32 s44, s45
	s_waitcnt lgkmcnt(0)
	s_barrier
	s_cbranch_vccz .LBB0_378
.LBB0_381:
	v_add_u32_e32 v217, v189, v190
	ds_read_b128 v[148:151], v217
	ds_read_b128 v[218:221], v194 offset:16384
	ds_read_b128 v[224:227], v194 offset:20480
	s_add_i32 s42, s44, 3
	s_cmp_ge_u32 s42, s35
	v_lshl_add_u64 v[152:153], v[140:141], 0, v[0:1]
	s_waitcnt lgkmcnt(1)
	v_mfma_f32_32x32x16_bf16 v[18:33], v[148:151], v[218:221], v[18:33]
	v_add_u32_e32 v219, v189, v191
	v_add_u32_e32 v218, v189, v192
	v_add_u32_e32 v220, v189, v193
	s_waitcnt lgkmcnt(0)
	v_mfma_f32_32x32x16_bf16 v[2:17], v[148:151], v[224:227], v[2:17]
	ds_read_b128 v[148:151], v219
	ds_read_b128 v[224:227], v195 offset:16384
	ds_read_b128 v[228:231], v195 offset:20480
	s_waitcnt lgkmcnt(1)
	v_mfma_f32_32x32x16_bf16 v[18:33], v[148:151], v[224:227], v[18:33]
	s_waitcnt lgkmcnt(0)
	v_mfma_f32_32x32x16_bf16 v[2:17], v[148:151], v[228:231], v[2:17]
	ds_read_b128 v[148:151], v218
	ds_read_b128 v[224:227], v196 offset:16384
	ds_read_b128 v[228:231], v196 offset:20480
	s_waitcnt lgkmcnt(1)
	v_mfma_f32_32x32x16_bf16 v[18:33], v[148:151], v[224:227], v[18:33]
	s_waitcnt lgkmcnt(0)
	v_mfma_f32_32x32x16_bf16 v[2:17], v[148:151], v[228:231], v[2:17]
	ds_read_b128 v[148:151], v220
	ds_read_b128 v[224:227], v197 offset:16384
	ds_read_b128 v[228:231], v197 offset:20480
	s_cmp_lg_u32 s44, 0
	s_cbranch_scc1 .Lpq_a1
	s_waitcnt vmcnt(39)
	ds_write_b128 v188, v[34:37] offset:32768
	s_waitcnt vmcnt(38)
	ds_write_b128 v188, v[38:41] offset:40960
	s_waitcnt vmcnt(35)
	ds_write_b128 v188, v[50:53] offset:49152
	s_waitcnt vmcnt(33)
	ds_write_b128 v188, v[58:61] offset:57344
	s_branch .Lpq_j1
.Lpq_a1:
	s_cmp_eq_u32 s44, 4
	s_cbranch_scc1 .Lpq_m1
	s_cmp_eq_u32 s44, 8
	s_cbranch_scc1 .Lpq_m1
	s_waitcnt vmcnt(3)
	ds_write_b128 v188, v[34:37] offset:32768
	s_waitcnt vmcnt(2)
	ds_write_b128 v188, v[38:41] offset:40960
	s_waitcnt vmcnt(1)
	ds_write_b128 v188, v[50:53] offset:49152
	s_waitcnt vmcnt(0)
	ds_write_b128 v188, v[58:61] offset:57344
	s_branch .Lpq_j1
.Lpq_m1:
	s_waitcnt vmcnt(39)
	ds_write_b128 v188, v[34:37] offset:32768
	s_waitcnt vmcnt(38)
	ds_write_b128 v188, v[38:41] offset:40960
	s_waitcnt vmcnt(37)
	ds_write_b128 v188, v[50:53] offset:49152
	s_waitcnt vmcnt(36)
	ds_write_b128 v188, v[58:61] offset:57344
.Lpq_j1:
	s_cmp_ge_u32 s42, s35
	s_waitcnt lgkmcnt(5)
	v_mfma_f32_32x32x16_bf16 v[18:33], v[148:151], v[224:227], v[18:33]
	s_waitcnt lgkmcnt(4)
	v_mfma_f32_32x32x16_bf16 v[2:17], v[148:151], v[228:231], v[2:17]
	v_lshl_add_u64 v[148:149], v[144:145], 0, v[0:1]
	v_lshl_add_u64 v[150:151], v[146:147], 0, v[0:1]
	s_cbranch_scc1 .LBB0_383
	v_lshl_add_u64 v[34:35], v[142:143], 0, v[0:1]
	global_load_dwordx4 v[34:37], v[34:35], off
	s_nop 0
	global_load_dwordx4 v[38:41], v[148:149], off
	global_load_dwordx4 v[50:53], v[150:151], off
	global_load_dwordx4 v[58:61], v[152:153], off
.LBB0_383:
	s_waitcnt lgkmcnt(0)
	s_barrier
	ds_read_b128 v[224:227], v217 offset:32768
	ds_read_b128 v[228:231], v194 offset:49152
	s_add_i32 s45, s44, 2
	s_waitcnt lgkmcnt(0)
	v_mfma_f32_32x32x16_bf16 v[18:33], v[224:227], v[228:231], v[18:33]
	ds_read_b128 v[228:231], v194 offset:53248
	s_cmp_ge_u32 s45, s35
	s_cselect_b64 s[42:43], -1, 0
	s_and_b64 vcc, exec, s[42:43]
	s_waitcnt lgkmcnt(0)
	v_mfma_f32_32x32x16_bf16 v[2:17], v[224:227], v[228:231], v[2:17]
	ds_read_b128 v[224:227], v219 offset:32768
	ds_read_b128 v[228:231], v195 offset:49152
	s_waitcnt lgkmcnt(0)
	v_mfma_f32_32x32x16_bf16 v[18:33], v[224:227], v[228:231], v[18:33]
	ds_read_b128 v[228:231], v195 offset:53248
	s_waitcnt lgkmcnt(0)
	v_mfma_f32_32x32x16_bf16 v[2:17], v[224:227], v[228:231], v[2:17]
	ds_read_b128 v[224:227], v218 offset:32768
	ds_read_b128 v[228:231], v196 offset:49152
	s_waitcnt lgkmcnt(0)
	v_mfma_f32_32x32x16_bf16 v[18:33], v[224:227], v[228:231], v[18:33]
	ds_read_b128 v[228:231], v196 offset:53248
	s_waitcnt lgkmcnt(0)
	v_mfma_f32_32x32x16_bf16 v[2:17], v[224:227], v[228:231], v[2:17]
	ds_read_b128 v[218:221], v220 offset:32768
	ds_read_b128 v[224:227], v197 offset:49152
	s_waitcnt lgkmcnt(0)
	v_mfma_f32_32x32x16_bf16 v[18:33], v[218:221], v[224:227], v[18:33]
	ds_read_b128 v[224:227], v197 offset:53248
	s_waitcnt lgkmcnt(0)
	v_mfma_f32_32x32x16_bf16 v[2:17], v[218:221], v[224:227], v[2:17]
	s_cbranch_vccnz .LBB0_385
	s_cmp_lg_u32 s44, 0
	s_cbranch_scc1 .Lpq_a2
	s_waitcnt vmcnt(41)
	ds_write_b128 v188, v[42:45]
	s_waitcnt vmcnt(40)
	ds_write_b128 v188, v[46:49] offset:8192
	s_waitcnt vmcnt(38)
	ds_write_b128 v188, v[54:57] offset:16384
	s_waitcnt vmcnt(36)
	ds_write_b128 v188, v[62:65] offset:24576
	s_branch .Lpq_j2
.Lpq_a2:
	s_cmp_eq_u32 s44, 4
	s_cbranch_scc1 .Lpq_m2
	s_cmp_eq_u32 s44, 8
	s_cbranch_scc1 .Lpq_m2
	ds_write_b128 v188, v[42:45]
	ds_write_b128 v188, v[46:49] offset:8192
	ds_write_b128 v188, v[54:57] offset:16384
	s_waitcnt vmcnt(0)
	ds_write_b128 v188, v[62:65] offset:24576
	s_branch .Lpq_j2
.Lpq_m2:
	s_waitcnt vmcnt(39)
	ds_write_b128 v188, v[42:45]
	s_waitcnt vmcnt(38)
	ds_write_b128 v188, v[46:49] offset:8192
	s_waitcnt vmcnt(37)
	ds_write_b128 v188, v[54:57] offset:16384
	s_waitcnt vmcnt(36)
	ds_write_b128 v188, v[62:65] offset:24576
.Lpq_j2:
.LBB0_385:
	s_add_i32 s44, s44, 4
	s_cmp_ge_u32 s44, s35
	s_cbranch_scc1 .LBB0_380
	v_lshl_add_u64 v[42:43], v[138:139], 0, v[0:1]
	global_load_dwordx4 v[42:45], v[42:43], off
	s_nop 0
	global_load_dwordx4 v[46:49], v[148:149], off offset:128
	global_load_dwordx4 v[54:57], v[150:151], off offset:128
	global_load_dwordx4 v[62:65], v[152:153], off offset:128
	s_branch .LBB0_380
